# MoBA stack: permlane32_swap exchanges + prefetch loads spread under QK MFMAs + static priority for waves 0-3
# speedup vs baseline: 1.0074x; 1.0013x over previous
; __global__ void __launch_bounds__(512, 2) mega_fwd(Params p) {
;     ...
;         for (int pair = blockIdx.x; pair < 256; pair += G) {
;             const int bh = pair >> 4, q16 = pair & 15;
;             moba_item(p, lds, bh >> 3, bh & 7, q16, 0);
;             moba_item(p, lds, bh >> 3, bh & 7, 15 - q16, 1);
;         }
.Lmoba_prio_done:
	s_cbranch_vccnz .LBB0_499
	v_readlane_b32 s21, v255, 15
	s_mov_b32 s22, s2
	s_mov_b32 s23, s2
	s_branch .LBB0_425

; #define LAS __attribute__((address_space(3)))
; #define MFMA32(a, b, c) __builtin_amdgcn_mfma_f32_32x32x16_bf16((a), (b), (c), 0, 0, 0)
; __device__ __forceinline__ int crow(int reg, int h) { return (reg & 3) + 8 * (reg >> 2) + 4 * h; }
; __device__ __forceinline__ void moba_item(const Params& p, LAS unsigned char* lds, int b, int h, int qb, int half) {
;     ...
;     for (int step = 0; step < nsteps; ++step) {
;         __syncthreads();
;         const int cb = (step & 1) * MB_BUF;
;         if (step + 1 < nsteps) {
;             const int nb = MB_BUF - cb;
; #pragma unroll
;             for (int i = 0; i < 4; ++i) { *(LAS u32x4*)(Kl + nb + (srow + 32 * i) * MB_KS + scol * 16) = kreg[i]; *(LAS u32x4*)(Vl + nb + (srow + 32 * i) * MB_VS + scol * 16) = vreg[i]; }
;             if (step + 2 < nsteps) { MOBA_ISSUE_K(step + 2); MOBA_ISSUE_V(step + 2); }
;         }
;         const int jj = step >> 1, blk = jj == 0 ? qb : jj - 1;
;         const bool own = jj == 0;
;         const bool sel = own || ((mymask >> blk) & 1u);
;         f32x16 s[2];
; #pragma unroll
;         for (int kt = 0; kt < 2; ++kt) {
;             bf16x8 af[8];
; #pragma unroll
;             for (int ks = 0; ks < 8; ++ks) af[ks] = *(const LAS bf16x8*)(Kl + cb + (64 * team + 32 * kt + r) * MB_KS + (16 * ks + 8 * hh) * 2);
;             __builtin_amdgcn_sched_barrier(0);
; #pragma unroll
;             for (int i = 0; i < 16; ++i) s[kt][i] = 0.f;
; #pragma unroll
;             for (int ks = 0; ks < 8; ++ks) s[kt] = MFMA32(af[ks], qf[ks], s[kt]);
;             __builtin_amdgcn_sched_barrier(0);
;         }
;         float tmax = -INFINITY;
;         const int kbase = (step & 1) * 128 + 64 * team;
;         if (own) {
;             asm volatile("" ::: "memory");
; #pragma unroll
;             for (int kt = 0; kt < 2; ++kt)
; #pragma unroll
;                 for (int i = 0; i < 16; ++i) {
;                     const int kl = kbase + 32 * kt + crow(i, hh);
;                     const float v = (kl <= qloc) ? s[kt][i] : -INFINITY;
;                     s[kt][i] = v; tmax = fmaxf(tmax, v);
;                 }
;         } else {
;             asm volatile("" ::: "memory");
; #pragma unroll
;             for (int kt = 0; kt < 2; ++kt)
; #pragma unroll
;                 for (int i = 0; i < 16; ++i) tmax = fmaxf(tmax, s[kt][i]);
;             tmax = sel ? tmax : -INFINITY;
.LBB0_446:
	s_bitcmp1_b32 s27, 0
	s_cselect_b32 s28, 0x12800, 0
	s_xor_b32 s0, s28, 0x12800
	v_add3_u32 v64, v172, s0, v174
	v_add3_u32 v65, v173, s0, v175
	s_cmp_ge_u32 s27, s12
	s_waitcnt lgkmcnt(0)
	s_barrier
	s_waitcnt vmcnt(7)
	ds_write_b128 v64, v[128:131]
	s_waitcnt vmcnt(3)
	ds_write_b128 v65, v[140:143]
	ds_write_b128 v64, v[132:135] offset:8704
	s_waitcnt vmcnt(2)
	ds_write_b128 v65, v[148:151] offset:10240
	ds_write_b128 v64, v[136:139] offset:17408
	s_waitcnt vmcnt(1)
	ds_write_b128 v65, v[152:155] offset:20480
	ds_write_b128 v64, v[144:147] offset:26112
	s_waitcnt vmcnt(0)
	ds_write_b128 v65, v[156:159] offset:30720
	v_add_co_u32_e32 v220, vcc, 0xd0000, v162
	s_nop 1
	v_addc_co_u32_e32 v221, vcc, 0, v163, vcc
	v_add_co_u32_e32 v222, vcc, 0x1a0000, v162
	s_nop 1
	v_addc_co_u32_e32 v223, vcc, 0, v163, vcc
	v_add_co_u32_e32 v224, vcc, 0x270000, v162
	s_nop 1
	v_addc_co_u32_e32 v225, vcc, 0, v163, vcc
.LBB0_448:
	s_lshr_b32 s0, s27, 1
	s_add_i32 s0, s0, -1
	s_lshl_b32 s0, 1, s0
	v_and_b32_e32 v64, s0, v170
	v_add_u32_e32 v161, s28, v178
	v_cmp_ne_u32_e64 s[6:7], 0, v64
	ds_read_b128 v[64:67], v161
	ds_read_b128 v[68:71], v161 offset:32
	ds_read_b128 v[72:75], v161 offset:64
	ds_read_b128 v[76:79], v161 offset:96
	ds_read_b128 v[184:187], v161 offset:128
	ds_read_b128 v[188:191], v161 offset:160
	ds_read_b128 v[194:197], v161 offset:192
	ds_read_b128 v[216:219], v161 offset:224
	s_waitcnt lgkmcnt(7)
	v_mfma_f32_32x32x16_bf16 v[80:95], v[64:67], v[124:127], 0
	global_load_dwordx4 v[128:131], v[162:163], off
	s_waitcnt lgkmcnt(6)
	v_mfma_f32_32x32x16_bf16 v[80:95], v[68:71], v[120:123], v[80:95]
	global_load_dwordx4 v[140:143], v[162:163], off offset:2048
	s_waitcnt lgkmcnt(5)
	v_mfma_f32_32x32x16_bf16 v[80:95], v[72:75], v[116:119], v[80:95]
	global_load_dwordx4 v[132:135], v[220:221], off
	s_waitcnt lgkmcnt(4)
	v_mfma_f32_32x32x16_bf16 v[80:95], v[76:79], v[112:115], v[80:95]
	global_load_dwordx4 v[148:151], v[220:221], off offset:2048
	s_waitcnt lgkmcnt(3)
	v_mfma_f32_32x32x16_bf16 v[80:95], v[184:187], v[108:111], v[80:95]
	global_load_dwordx4 v[136:139], v[222:223], off
	s_waitcnt lgkmcnt(2)
	v_mfma_f32_32x32x16_bf16 v[80:95], v[188:191], v[104:107], v[80:95]
	global_load_dwordx4 v[152:155], v[222:223], off offset:2048
	s_waitcnt lgkmcnt(1)
	v_mfma_f32_32x32x16_bf16 v[80:95], v[194:197], v[100:103], v[80:95]
	global_load_dwordx4 v[144:147], v[224:225], off
	s_waitcnt lgkmcnt(0)
	v_mfma_f32_32x32x16_bf16 v[80:95], v[216:219], v[96:99], v[80:95]
	global_load_dwordx4 v[156:159], v[224:225], off offset:2048
	ds_read_b128 v[64:67], v161 offset:8704
	ds_read_b128 v[184:187], v161 offset:8736
	ds_read_b128 v[188:191], v161 offset:8768
	ds_read_b128 v[194:197], v161 offset:8800
	ds_read_b128 v[216:219], v161 offset:8832
	ds_read_b128 v[220:223], v161 offset:8864
	ds_read_b128 v[224:227], v161 offset:8896
	ds_read_b128 v[228:231], v161 offset:8928
	s_waitcnt lgkmcnt(7)
	v_mfma_f32_32x32x16_bf16 v[64:79], v[64:67], v[124:127], 0
	s_waitcnt lgkmcnt(6)
	v_mfma_f32_32x32x16_bf16 v[64:79], v[184:187], v[120:123], v[64:79]
	s_waitcnt lgkmcnt(5)
	v_mfma_f32_32x32x16_bf16 v[64:79], v[188:191], v[116:119], v[64:79]
	s_waitcnt lgkmcnt(4)
	v_mfma_f32_32x32x16_bf16 v[64:79], v[194:197], v[112:115], v[64:79]
	s_waitcnt lgkmcnt(3)
	v_mfma_f32_32x32x16_bf16 v[64:79], v[216:219], v[108:111], v[64:79]
	s_waitcnt lgkmcnt(2)
	v_mfma_f32_32x32x16_bf16 v[64:79], v[220:223], v[104:107], v[64:79]
	s_waitcnt lgkmcnt(1)
	v_mfma_f32_32x32x16_bf16 v[64:79], v[224:227], v[100:103], v[64:79]
	s_waitcnt lgkmcnt(0)
	v_mfma_f32_32x32x16_bf16 v[64:79], v[228:231], v[96:99], v[64:79]
	s_cmp_lt_u32 s27, 2
	s_cselect_b64 s[0:1], -1, 0
	s_cmp_gt_u32 s27, 1
	s_mov_b64 s[14:15], -1
	s_cbranch_scc0 .LBB0_450
	v_max3_f32 v161, v80, s84, v81
	v_max3_f32 v161, v161, v82, v83
	v_max3_f32 v161, v161, v84, v85
	v_max3_f32 v161, v161, v86, v87
	v_max3_f32 v161, v161, v88, v89
	v_max3_f32 v161, v161, v90, v91
	v_max3_f32 v161, v161, v92, v93
	v_max3_f32 v161, v161, v94, v95
	v_max3_f32 v161, v161, v64, v65
	v_max3_f32 v161, v161, v66, v67
	v_max3_f32 v161, v161, v68, v69
	v_max3_f32 v161, v161, v70, v71
	v_max3_f32 v161, v161, v72, v73
	v_max3_f32 v161, v161, v74, v75
	v_max3_f32 v161, v161, v76, v77
	v_max3_f32 v161, v161, v78, v79
	v_cndmask_b32_e64 v181, v240, v161, s[6:7]
	s_mov_b64 s[14:15], 0

; #define LAS __attribute__((address_space(3)))
; #define MFMA32(a, b, c) __builtin_amdgcn_mfma_f32_32x32x16_bf16((a), (b), (c), 0, 0, 0)
; __device__ __forceinline__ int crow(int reg, int h) { return (reg & 3) + 8 * (reg >> 2) + 4 * h; }
; __device__ __forceinline__ void moba_item(const Params& p, LAS unsigned char* lds, int b, int h, int qb, int half) {
;     ...
;     for (int step = 0; step < nsteps; ++step) {
;         __syncthreads();
;         const int cb = (step & 1) * MB_BUF;
;         if (step + 1 < nsteps) {
;             const int nb = MB_BUF - cb;
; #pragma unroll
;             for (int i = 0; i < 4; ++i) { *(LAS u32x4*)(Kl + nb + (srow + 32 * i) * MB_KS + scol * 16) = kreg[i]; *(LAS u32x4*)(Vl + nb + (srow + 32 * i) * MB_VS + scol * 16) = vreg[i]; }
;             if (step + 2 < nsteps) { MOBA_ISSUE_K(step + 2); MOBA_ISSUE_V(step + 2); }
;         }
;         const int jj = step >> 1, blk = jj == 0 ? qb : jj - 1;
;         const bool own = jj == 0;
;         const bool sel = own || ((mymask >> blk) & 1u);
;         f32x16 s[2];
; #pragma unroll
;         for (int kt = 0; kt < 2; ++kt) {
;             bf16x8 af[8];
; #pragma unroll
;             for (int ks = 0; ks < 8; ++ks) af[ks] = *(const LAS bf16x8*)(Kl + cb + (64 * team + 32 * kt + r) * MB_KS + (16 * ks + 8 * hh) * 2);
;             __builtin_amdgcn_sched_barrier(0);
; #pragma unroll
;             for (int i = 0; i < 16; ++i) s[kt][i] = 0.f;
; #pragma unroll
;             for (int ks = 0; ks < 8; ++ks) s[kt] = MFMA32(af[ks], qf[ks], s[kt]);
;             __builtin_amdgcn_sched_barrier(0);
;         }
;         float tmax = -INFINITY;
;         const int kbase = (step & 1) * 128 + 64 * team;
;         if (own) {
;             asm volatile("" ::: "memory");
; #pragma unroll
;             for (int kt = 0; kt < 2; ++kt)
; #pragma unroll
;                 for (int i = 0; i < 16; ++i) {
;                     const int kl = kbase + 32 * kt + crow(i, hh);
;                     const float v = (kl <= qloc) ? s[kt][i] : -INFINITY;
;                     s[kt][i] = v; tmax = fmaxf(tmax, v);
;                 }
;         } else {
;             asm volatile("" ::: "memory");
; #pragma unroll
;             for (int kt = 0; kt < 2; ++kt)
; #pragma unroll
;                 for (int i = 0; i < 16; ++i) tmax = fmaxf(tmax, s[kt][i]);
;             tmax = sel ? tmax : -INFINITY;
.LBB0_483:
	s_bitcmp1_b32 s14, 0
	s_cselect_b32 s16, 0x12800, 0
	s_xor_b32 s6, s16, 0x12800
	v_add_u32_e32 v65, 0x8800, v172
	v_add3_u32 v64, v172, s6, v173
	v_add3_u32 v65, v65, s6, v174
	s_cmp_ge_u32 s14, s15
	s_waitcnt lgkmcnt(0)
	s_barrier
	s_waitcnt vmcnt(7)
	ds_write_b128 v64, v[128:131]
	s_waitcnt vmcnt(3)
	ds_write_b128 v65, v[144:147]
	ds_write_b128 v64, v[132:135] offset:8704
	s_waitcnt vmcnt(2)
	ds_write_b128 v65, v[148:151] offset:10240
	ds_write_b128 v64, v[136:139] offset:17408
	s_waitcnt vmcnt(1)
	ds_write_b128 v65, v[152:155] offset:20480
	ds_write_b128 v64, v[140:143] offset:26112
	s_waitcnt vmcnt(0)
	ds_write_b128 v65, v[156:159] offset:30720
	v_lshl_add_u64 v[228:229], v[162:163], 0, s[0:1]
.LBB0_485:
	s_lshr_b32 s6, s14, 1
	s_add_i32 s6, s6, -1
	s_lshl_b32 s6, 1, s6
	v_and_b32_e32 v64, s6, v171
	v_add_u32_e32 v187, s16, v183
	v_cmp_ne_u32_e64 s[6:7], 0, v64
	ds_read_b128 v[64:67], v187
	ds_read_b128 v[68:71], v187 offset:32
	ds_read_b128 v[72:75], v187 offset:64
	ds_read_b128 v[76:79], v187 offset:96
	ds_read_b128 v[194:197], v187 offset:128
	ds_read_b128 v[216:219], v187 offset:160
	ds_read_b128 v[220:223], v187 offset:192
	ds_read_b128 v[224:227], v187 offset:224
	s_waitcnt lgkmcnt(7)
	v_mfma_f32_32x32x16_bf16 v[80:95], v[64:67], v[124:127], 0
	v_add_co_u32_e32 v230, vcc, 0x18400000, v228
	s_nop 1
	v_addc_co_u32_e32 v231, vcc, 0, v229, vcc
	v_add_co_u32_e32 v244, vcc, 0x184d0000, v228
	s_nop 1
	v_addc_co_u32_e32 v245, vcc, 0, v229, vcc
	global_load_dwordx4 v[128:131], v[230:231], off offset:2048
	s_waitcnt lgkmcnt(6)
	v_mfma_f32_32x32x16_bf16 v[80:95], v[68:71], v[120:123], v[80:95]
	global_load_dwordx4 v[132:135], v[244:245], off offset:2048
	s_waitcnt lgkmcnt(5)
	v_mfma_f32_32x32x16_bf16 v[80:95], v[72:75], v[116:119], v[80:95]
	v_add_co_u32_e32 v230, vcc, 0x185a0000, v228
	s_nop 1
	v_addc_co_u32_e32 v231, vcc, 0, v229, vcc
	v_add_co_u32_e32 v244, vcc, 0x18670000, v228
	s_nop 1
	v_addc_co_u32_e32 v245, vcc, 0, v229, vcc
	global_load_dwordx4 v[136:139], v[230:231], off offset:2048
	s_waitcnt lgkmcnt(4)
	v_mfma_f32_32x32x16_bf16 v[80:95], v[76:79], v[112:115], v[80:95]
	global_load_dwordx4 v[140:143], v[244:245], off offset:2048
	s_waitcnt lgkmcnt(3)
	v_mfma_f32_32x32x16_bf16 v[80:95], v[194:197], v[108:111], v[80:95]
	v_add_co_u32_e32 v230, vcc, 0x18401000, v228
	s_nop 1
	v_addc_co_u32_e32 v231, vcc, 0, v229, vcc
	v_add_co_u32_e32 v244, vcc, 0x184d1000, v228
	s_nop 1
	v_addc_co_u32_e32 v245, vcc, 0, v229, vcc
	global_load_dwordx4 v[144:147], v[230:231], off
	s_waitcnt lgkmcnt(2)
	v_mfma_f32_32x32x16_bf16 v[80:95], v[216:219], v[104:107], v[80:95]
	global_load_dwordx4 v[148:151], v[244:245], off
	s_waitcnt lgkmcnt(1)
	v_mfma_f32_32x32x16_bf16 v[80:95], v[220:223], v[100:103], v[80:95]
	v_add_co_u32_e32 v230, vcc, 0x185a1000, v228
	s_nop 1
	v_addc_co_u32_e32 v231, vcc, 0, v229, vcc
	v_add_co_u32_e32 v244, vcc, 0x18671000, v228
	s_nop 1
	v_addc_co_u32_e32 v245, vcc, 0, v229, vcc
	global_load_dwordx4 v[152:155], v[230:231], off
	s_waitcnt lgkmcnt(0)
	v_mfma_f32_32x32x16_bf16 v[80:95], v[224:227], v[96:99], v[80:95]
	global_load_dwordx4 v[156:159], v[244:245], off
	ds_read_b128 v[64:67], v187 offset:8704
	ds_read_b128 v[194:197], v187 offset:8736
	ds_read_b128 v[216:219], v187 offset:8768
	ds_read_b128 v[220:223], v187 offset:8800
	ds_read_b128 v[224:227], v187 offset:8832
	ds_read_b128 v[228:231], v187 offset:8864
	ds_read_b128 v[244:247], v187 offset:8896
	ds_read_b128 v[248:251], v187 offset:8928
	s_waitcnt lgkmcnt(7)
	v_mfma_f32_32x32x16_bf16 v[64:79], v[64:67], v[124:127], 0
	s_waitcnt lgkmcnt(6)
	v_mfma_f32_32x32x16_bf16 v[64:79], v[194:197], v[120:123], v[64:79]
	s_waitcnt lgkmcnt(5)
	v_mfma_f32_32x32x16_bf16 v[64:79], v[216:219], v[116:119], v[64:79]
	s_waitcnt lgkmcnt(4)
	v_mfma_f32_32x32x16_bf16 v[64:79], v[220:223], v[112:115], v[64:79]
	s_waitcnt lgkmcnt(3)
	v_mfma_f32_32x32x16_bf16 v[64:79], v[224:227], v[108:111], v[64:79]
	s_waitcnt lgkmcnt(2)
	v_mfma_f32_32x32x16_bf16 v[64:79], v[228:231], v[104:107], v[64:79]
	s_waitcnt lgkmcnt(1)
	v_mfma_f32_32x32x16_bf16 v[64:79], v[244:247], v[100:103], v[64:79]
	s_waitcnt lgkmcnt(0)
	v_mfma_f32_32x32x16_bf16 v[64:79], v[248:251], v[96:99], v[64:79]
	s_cmp_lt_u32 s14, 2
	s_cselect_b64 s[8:9], -1, 0
	s_cmp_gt_u32 s14, 1
	s_mov_b64 s[10:11], -1
	s_cbranch_scc0 .LBB0_487
	v_max3_f32 v187, v80, s84, v81
	v_max3_f32 v187, v187, v82, v83
	v_max3_f32 v187, v187, v84, v85
	v_max3_f32 v187, v187, v86, v87
	v_max3_f32 v187, v187, v88, v89
	v_max3_f32 v187, v187, v90, v91
	v_max3_f32 v187, v187, v92, v93
	v_max3_f32 v187, v187, v94, v95
	v_max3_f32 v187, v187, v64, v65
	v_max3_f32 v187, v187, v66, v67
	v_max3_f32 v187, v187, v68, v69
	v_max3_f32 v187, v187, v70, v71
	v_max3_f32 v187, v187, v72, v73
	v_max3_f32 v187, v187, v74, v75
	v_max3_f32 v187, v187, v76, v77
	v_max3_f32 v187, v187, v78, v79
	v_cndmask_b32_e64 v187, v240, v187, s[6:7]
	s_mov_b64 s[10:11], 0
